# v026 + loop-top more2 flags formed with s_cselect instead of a v_cndmask/v_cmp round trip (7 attention loops)
# speedup vs baseline: 1.0111x; 1.0111x over previous
; template <bool HAS_POST, class MaskF>
; __device__ __forceinline__ void attn_run(LAS unsigned char* lds, const bf16* Kg, const bf16* Vg, int pitch, int t0, int t1,
;                                          const bf16x8 (&qr)[4], f32x16& o0, f32x16& o1, f32x16& o2, MaskF& mf, const int wv) {
;     ...
;     for (int ts = t0; ts < t1; ts += 2) {
;         const int cur = ((ts - t0) >> 1) & 1;
;         const bool more = (ts + 2 < t1), more2 = (ts + 3 < t1);
;         if (more) { kp += 2 * tstride; kreg0 = *(const v4u*)kp; vp += 2 * tstride; vreg0 = *(const v4u*)vp;
;             if (more2) { kreg1 = *(const v4u*)(kp + tstride); vreg1 = *(const v4u*)(vp + tstride); } }
.LBB0_851:
	s_add_i32 s0, s16, -2
	s_cmp_lt_i32 s16, s34
	s_cselect_b64 s[14:15], -1, 0
	s_cmp_ge_i32 s16, s34
	s_cselect_b64 s[12:13], -1, 0
	s_cmp_lt_i32 s0, s22
	s_cselect_b64 s[4:5], -1, 0
	s_cselect_b64 s[6:7], 0, exec
	s_and_b64 vcc, exec, s[12:13]
	s_cbranch_vccnz .LBB0_855
	s_mov_b64 s[4:5], 0x4000
	v_lshl_add_u64 v[154:155], v[154:155], 0, s[4:5]
	v_lshl_add_u64 v[156:157], v[156:157], 0, s[4:5]
	global_load_dwordx4 v[82:85], v[154:155], off
	global_load_dwordx4 v[86:89], v[156:157], off
	s_and_b64 vcc, exec, s[6:7]
	s_cbranch_vccnz .LBB0_854
	s_mov_b64 s[4:5], 0x2000
	v_lshl_add_u64 v[50:51], v[154:155], 0, s[4:5]
	global_load_dwordx4 v[90:93], v[50:51], off
	v_lshl_add_u64 v[50:51], v[156:157], 0, s[4:5]
	global_load_dwordx4 v[94:97], v[50:51], off

; template <bool HAS_POST, class MaskF>
; __device__ __forceinline__ void attn_run(LAS unsigned char* lds, const bf16* Kg, const bf16* Vg, int pitch, int t0, int t1,
;                                          const bf16x8 (&qr)[4], f32x16& o0, f32x16& o1, f32x16& o2, MaskF& mf, const int wv) {
;     ...
;     for (int ts = t0; ts < t1; ts += 2) {
;         const int cur = ((ts - t0) >> 1) & 1;
;         const bool more = (ts + 2 < t1), more2 = (ts + 3 < t1);
;         if (more) { kp += 2 * tstride; kreg0 = *(const v4u*)kp; vp += 2 * tstride; vreg0 = *(const v4u*)vp;
;             if (more2) { kreg1 = *(const v4u*)(kp + tstride); vreg1 = *(const v4u*)(vp + tstride); } }
.LBB0_921:
	s_add_u32 s94, s4, 2
	s_addc_u32 s95, s5, 0
	s_cmp_gt_i32 s94, s38
	s_cselect_b64 s[20:21], -1, 0
	s_cmp_le_i32 s94, s38
	s_cselect_b64 s[96:97], -1, 0
	s_cmp_lt_i32 s4, s23
	s_cselect_b64 s[0:1], -1, 0
	s_cselect_b64 s[92:93], 0, exec
	s_and_b64 vcc, exec, s[20:21]
	s_cbranch_vccnz .LBB0_925
	s_mov_b64 s[0:1], 0xc0000
	v_lshl_add_u64 v[154:155], v[154:155], 0, s[0:1]
	v_lshl_add_u64 v[156:157], v[156:157], 0, s[0:1]
	global_load_dwordx4 v[82:85], v[154:155], off
	global_load_dwordx4 v[86:89], v[156:157], off
	s_and_b64 vcc, exec, s[92:93]
	s_cbranch_vccnz .LBB0_924
	s_mov_b64 s[0:1], 0x60000
	v_lshl_add_u64 v[50:51], v[154:155], 0, s[0:1]
	global_load_dwordx4 v[90:93], v[50:51], off
	v_lshl_add_u64 v[50:51], v[156:157], 0, s[0:1]
	global_load_dwordx4 v[94:97], v[50:51], off

; template <bool HAS_POST, class MaskF>
; __device__ __forceinline__ void attn_run(LAS unsigned char* lds, const bf16* Kg, const bf16* Vg, int pitch, int t0, int t1,
;                                          const bf16x8 (&qr)[4], f32x16& o0, f32x16& o1, f32x16& o2, MaskF& mf, const int wv) {
;     ...
;     for (int ts = t0; ts < t1; ts += 2) {
;         const int cur = ((ts - t0) >> 1) & 1;
;         const bool more = (ts + 2 < t1), more2 = (ts + 3 < t1);
;         if (more) { kp += 2 * tstride; kreg0 = *(const v4u*)kp; vp += 2 * tstride; vreg0 = *(const v4u*)vp;
;             if (more2) { kreg1 = *(const v4u*)(kp + tstride); vreg1 = *(const v4u*)(vp + tstride); } }
.LBB0_960:
	s_add_i32 s1, s3, s96
	s_add_i32 s0, s1, -8
	s_add_i32 s1, s1, -6
	s_cmp_le_i32 s1, s38
	s_cselect_b64 s[20:21], -1, 0
	s_cmp_lt_i32 s0, s23
	s_cselect_b64 s[4:5], -1, 0
	s_cselect_b64 s[94:95], 0, exec
	s_cmp_gt_i32 s1, s38
	s_cbranch_scc1 .LBB0_964
	s_mov_b64 s[4:5], 0xc0000
	v_lshl_add_u64 v[198:199], v[198:199], 0, s[4:5]
	v_lshl_add_u64 v[200:201], v[200:201], 0, s[4:5]
	global_load_dwordx4 v[132:135], v[198:199], off
	global_load_dwordx4 v[136:139], v[200:201], off
	s_and_b64 vcc, exec, s[94:95]
	s_cbranch_vccnz .LBB0_963
	s_mov_b64 s[4:5], 0x60000
	v_lshl_add_u64 v[50:51], v[198:199], 0, s[4:5]
	global_load_dwordx4 v[140:143], v[50:51], off
	v_lshl_add_u64 v[50:51], v[200:201], 0, s[4:5]
	global_load_dwordx4 v[144:147], v[50:51], off

; template <bool HAS_POST, class MaskF>
; __device__ __forceinline__ void attn_run(LAS unsigned char* lds, const bf16* Kg, const bf16* Vg, int pitch, int t0, int t1,
;                                          const bf16x8 (&qr)[4], f32x16& o0, f32x16& o1, f32x16& o2, MaskF& mf, const int wv) {
;     ...
;     for (int ts = t0; ts < t1; ts += 2) {
;         const int cur = ((ts - t0) >> 1) & 1;
;         const bool more = (ts + 2 < t1), more2 = (ts + 3 < t1);
;         if (more) { kp += 2 * tstride; kreg0 = *(const v4u*)kp; vp += 2 * tstride; vreg0 = *(const v4u*)vp;
;             if (more2) { kreg1 = *(const v4u*)(kp + tstride); vreg1 = *(const v4u*)(vp + tstride); } }
.LBB0_1007:
	s_add_i32 s0, s16, -2
	s_cmp_lt_i32 s16, s33
	s_cselect_b64 s[14:15], -1, 0
	s_cmp_ge_i32 s16, s33
	s_cselect_b64 s[12:13], -1, 0
	s_cmp_lt_i32 s0, s2
	s_cselect_b64 s[4:5], -1, 0
	s_cselect_b64 s[6:7], 0, exec
	s_and_b64 vcc, exec, s[12:13]
	s_cbranch_vccnz .LBB0_1011
	s_mov_b64 s[4:5], 0x4000
	v_lshl_add_u64 v[154:155], v[154:155], 0, s[4:5]
	v_lshl_add_u64 v[156:157], v[156:157], 0, s[4:5]
	global_load_dwordx4 v[82:85], v[154:155], off
	global_load_dwordx4 v[86:89], v[156:157], off
	s_and_b64 vcc, exec, s[6:7]
	s_cbranch_vccnz .LBB0_1010
	s_mov_b64 s[4:5], 0x2000
	v_lshl_add_u64 v[50:51], v[154:155], 0, s[4:5]
	global_load_dwordx4 v[90:93], v[50:51], off
	v_lshl_add_u64 v[50:51], v[156:157], 0, s[4:5]
	global_load_dwordx4 v[94:97], v[50:51], off

; template <bool HAS_POST, class MaskF>
; __device__ __forceinline__ void attn_run(LAS unsigned char* lds, const bf16* Kg, const bf16* Vg, int pitch, int t0, int t1,
;                                          const bf16x8 (&qr)[4], f32x16& o0, f32x16& o1, f32x16& o2, MaskF& mf, const int wv) {
;     ...
;     for (int ts = t0; ts < t1; ts += 2) {
;         const int cur = ((ts - t0) >> 1) & 1;
;         const bool more = (ts + 2 < t1), more2 = (ts + 3 < t1);
;         if (more) { kp += 2 * tstride; kreg0 = *(const v4u*)kp; vp += 2 * tstride; vreg0 = *(const v4u*)vp;
;             if (more2) { kreg1 = *(const v4u*)(kp + tstride); vreg1 = *(const v4u*)(vp + tstride); } }
.LBB0_1077:
	s_add_u32 s94, s4, 2
	s_addc_u32 s95, s5, 0
	s_cmp_gt_i32 s94, s39
	s_cselect_b64 s[20:21], -1, 0
	s_cmp_le_i32 s94, s39
	s_cselect_b64 s[96:97], -1, 0
	s_cmp_lt_i32 s4, s27
	s_cselect_b64 s[0:1], -1, 0
	s_cselect_b64 s[92:93], 0, exec
	s_and_b64 vcc, exec, s[20:21]
	s_cbranch_vccnz .LBB0_1081
	s_mov_b64 s[0:1], 0xc0000
	v_lshl_add_u64 v[154:155], v[154:155], 0, s[0:1]
	v_lshl_add_u64 v[156:157], v[156:157], 0, s[0:1]
	global_load_dwordx4 v[82:85], v[154:155], off
	global_load_dwordx4 v[86:89], v[156:157], off
	s_and_b64 vcc, exec, s[92:93]
	s_cbranch_vccnz .LBB0_1080
	s_mov_b64 s[0:1], 0x60000
	v_lshl_add_u64 v[50:51], v[154:155], 0, s[0:1]
	global_load_dwordx4 v[90:93], v[50:51], off
	v_lshl_add_u64 v[50:51], v[156:157], 0, s[0:1]
	global_load_dwordx4 v[94:97], v[50:51], off

; template <bool HAS_POST, class MaskF>
; __device__ __forceinline__ void attn_run(LAS unsigned char* lds, const bf16* Kg, const bf16* Vg, int pitch, int t0, int t1,
;                                          const bf16x8 (&qr)[4], f32x16& o0, f32x16& o1, f32x16& o2, MaskF& mf, const int wv) {
;     ...
;     for (int ts = t0; ts < t1; ts += 2) {
;         const int cur = ((ts - t0) >> 1) & 1;
;         const bool more = (ts + 2 < t1), more2 = (ts + 3 < t1);
;         if (more) { kp += 2 * tstride; kreg0 = *(const v4u*)kp; vp += 2 * tstride; vreg0 = *(const v4u*)vp;
;             if (more2) { kreg1 = *(const v4u*)(kp + tstride); vreg1 = *(const v4u*)(vp + tstride); } }
.LBB0_1116:
	s_add_i32 s1, s35, s96
	s_add_i32 s0, s1, -8
	s_add_i32 s1, s1, -6
	s_cmp_le_i32 s1, s39
	s_cselect_b64 s[20:21], -1, 0
	s_cmp_lt_i32 s0, s27
	s_cselect_b64 s[4:5], -1, 0
	s_cselect_b64 s[94:95], 0, exec
	s_cmp_gt_i32 s1, s39
	s_cbranch_scc1 .LBB0_1120
	s_mov_b64 s[4:5], 0xc0000
	v_lshl_add_u64 v[198:199], v[198:199], 0, s[4:5]
	v_lshl_add_u64 v[200:201], v[200:201], 0, s[4:5]
	global_load_dwordx4 v[132:135], v[198:199], off
	global_load_dwordx4 v[136:139], v[200:201], off
	s_and_b64 vcc, exec, s[94:95]
	s_cbranch_vccnz .LBB0_1119
	s_mov_b64 s[4:5], 0x60000
	v_lshl_add_u64 v[50:51], v[198:199], 0, s[4:5]
	global_load_dwordx4 v[140:143], v[50:51], off
	v_lshl_add_u64 v[50:51], v[200:201], 0, s[4:5]
	global_load_dwordx4 v[144:147], v[50:51], off
